# GLA item start: dead address arithmetic of the removed c_r row loads deleted (23 VALU, mostly 64-bit shifts/adds)
# baseline (speedup 1.0000x reference)
.LBB0_190:
	s_cmpk_gt_i32 s20, 0xff
	s_mov_b64 s[2:3], -1
	s_cbranch_scc0 .LBB0_292
	s_lshl_b32 s6, s20, 1
	s_cmpk_gt_u32 s20, 0x2ff
	s_cbranch_scc0 .LBB0_231
	v_mov_b32_e32 v0, v206
	s_add_i32 s2, s6, 0xfffffa00
	v_ashrrev_i32_e32 v0, 8, v0
	v_mov_b32_e32 v106, v206
	v_mov_b32_e32 v111, v206
	v_add_u32_e32 v102, s2, v0
	v_readlane_b32 s4, v254, 15
	v_readlane_b32 s5, v254, 16
	v_lshlrev_b32_e32 v144, 6, v102
	v_and_b32_e32 v144, 0x1fc0, v144
	v_lshrrev_b32_e32 v145, 9, v102
	v_lshl_or_b32 v144, v145, 13, v144
	v_bfe_u32 v145, v206, 6, 2
	v_lshl_add_u32 v144, v145, 4, v144
	v_and_b32_e32 v145, 15, v206
	v_or_b32_e32 v144, v144, v145
	v_bfe_u32 v145, v206, 4, 2
	v_lshlrev_b32_e32 v144, 6, v144
	v_lshl_add_u32 v144, v145, 4, v144
	v_bfe_u32 v146, v102, 7, 2
	v_lshlrev_b32_e32 v146, 7, v146
	v_lshl_add_u32 v146, v145, 11, v146
	v_and_b32_e32 v147, 15, v206
	v_lshl_add_u32 v146, v147, 2, v146
	global_load_dwordx4 v[140:143], v144, s[4:5]
	global_load_dword v118, v146, s[82:83]
	global_load_dword v119, v146, s[82:83] offset:64
	global_load_dword v120, v146, s[82:83] offset:512
	global_load_dword v121, v146, s[82:83] offset:576
	global_load_dword v122, v146, s[82:83] offset:1024
	global_load_dword v123, v146, s[82:83] offset:1088
	global_load_dword v124, v146, s[82:83] offset:1536
	global_load_dword v125, v146, s[82:83] offset:1600
	v_mov_b32_e32 v1, v206
	v_bfe_u32 v2, v111, 6, 2
	s_movk_i32 s2, 0x100
	v_ashrrev_i32_e32 v0, 9, v102
	v_xor_b32_e32 v3, 3, v2
	v_cmp_gt_u32_e32 vcc, s2, v1
	v_ashrrev_i32_e32 v1, 31, v0
	v_and_b32_e32 v107, 15, v111
	v_cndmask_b32_e32 v108, v3, v2, vcc
	v_lshlrev_b64 v[100:101], 13, v[0:1]
	v_lshlrev_b32_e32 v0, 6, v102
	s_movk_i32 s2, 0x1fc0
	v_lshlrev_b32_e32 v113, 4, v108
	v_and_or_b32 v12, v0, s2, v100
	v_or_b32_e32 v110, v113, v107
	v_or_b32_e32 v100, v12, v110
	v_mov_b64_e32 v[0:1], s[68:69]
	v_bfe_u32 v8, v102, 7, 2
	v_mad_u64_u32 v[0:1], s[2:3], v100, s13, v[0:1]
	v_bfe_u32 v112, v111, 4, 2
	v_mad_i32_i24 v1, v101, s13, v1
	v_lshlrev_b32_e32 v176, 6, v8
	v_lshl_add_u64 v[0:1], v[0:1], 0, v[176:177]
	v_lshlrev_b32_e32 v2, 4, v112
	v_mov_b32_e32 v3, v177
	v_lshl_add_u64 v[0:1], v[0:1], 0, v[2:3]
	s_mov_b32 s2, 0x3e80000
	v_add_co_u32_e32 v0, vcc, s2, v0
	v_mov_b32_e32 v115, v206
	s_nop 0
	v_addc_co_u32_e32 v1, vcc, 0, v1, vcc
	global_load_dwordx4 v[0:3], v[0:1], off offset:3584
	v_lshlrev_b32_e32 v104, 7, v8
	v_bfe_u32 v116, v115, 2, 6
	v_lshlrev_b32_e32 v4, 4, v115
	v_and_b32_e32 v117, 48, v4
	v_or_b32_e32 v6, v12, v116
	v_mov_b64_e32 v[4:5], s[76:77]
	v_bfe_u32 v103, v115, 5, 3
	v_mad_u64_u32 v[6:7], s[2:3], v6, s13, v[4:5]
	v_mad_i32_i24 v7, v101, s13, v7
	v_mov_b32_e32 v105, v177
	v_lshlrev_b32_e32 v114, 3, v103
	v_lshlrev_b32_e32 v109, 5, v8
	v_lshl_add_u64 v[6:7], v[6:7], 0, v[104:105]
	v_lshlrev_b32_e32 v8, 1, v117
	v_mov_b32_e32 v9, v177
	v_or_b32_e32 v167, 1, v114
	v_lshl_add_u64 v[6:7], v[6:7], 0, v[8:9]
	s_mov_b64 s[2:3], 0x1000
	v_or_b32_e32 v8, v114, v12
	v_or_b32_e32 v12, v12, v167
	v_lshl_add_u64 v[158:159], v[6:7], 0, s[2:3]
	v_mad_u64_u32 v[12:13], s[2:3], v12, s13, v[4:5]
	v_and_b32_e32 v166, 31, v115
	v_readlane_b32 s4, v254, 15
	v_mad_i32_i24 v13, v101, s13, v13
	v_readlane_b32 s5, v254, 16
	v_lshlrev_b32_e32 v40, 1, v166
	v_mov_b32_e32 v41, v177
	v_lshl_add_u64 v[12:13], v[12:13], 0, v[176:177]
	v_lshl_add_u64 v[42:43], v[12:13], 0, v[40:41]
	v_or_b32_e32 v12, 2, v8
	v_mad_u64_u32 v[12:13], s[2:3], v12, s13, v[4:5]
	v_mad_i32_i24 v13, v101, s13, v13
	v_lshl_add_u64 v[12:13], v[12:13], 0, v[176:177]
	v_lshl_add_u64 v[58:59], v[12:13], 0, v[40:41]
	v_or_b32_e32 v12, 3, v8
	v_mad_u64_u32 v[12:13], s[2:3], v12, s13, v[4:5]
	v_mad_i32_i24 v13, v101, s13, v13
	v_lshl_add_u64 v[12:13], v[12:13], 0, v[176:177]
	v_lshl_add_u64 v[84:85], v[12:13], 0, v[40:41]
	v_or_b32_e32 v12, 4, v8
	v_mad_u64_u32 v[12:13], s[2:3], v12, s13, v[4:5]
	v_mad_i32_i24 v13, v101, s13, v13
	v_lshl_add_u64 v[12:13], v[12:13], 0, v[176:177]
	v_lshl_add_u64 v[156:157], v[12:13], 0, v[40:41]
	v_or_b32_e32 v12, 5, v8
	v_mad_u64_u32 v[12:13], s[2:3], v12, s13, v[4:5]
	v_mad_i32_i24 v13, v101, s13, v13
	v_lshl_add_u64 v[12:13], v[12:13], 0, v[176:177]
	v_lshl_add_u64 v[160:161], v[12:13], 0, v[40:41]
	v_or_b32_e32 v12, 6, v8
	v_mad_u64_u32 v[10:11], s[2:3], v8, s13, v[4:5]
	v_mad_u64_u32 v[12:13], s[2:3], v12, s13, v[4:5]
	v_or_b32_e32 v8, 7, v8
	v_mad_i32_i24 v13, v101, s13, v13
	v_mad_u64_u32 v[4:5], s[2:3], v8, s13, v[4:5]
	v_mad_i32_i24 v11, v101, s13, v11
	v_lshl_add_u64 v[12:13], v[12:13], 0, v[176:177]
	v_mad_i32_i24 v5, v101, s13, v5
	s_movk_i32 s2, 0x1000
	v_lshl_add_u64 v[10:11], v[10:11], 0, v[176:177]
	v_lshl_add_u64 v[164:165], v[12:13], 0, v[40:41]
	v_lshl_add_u64 v[4:5], v[4:5], 0, v[176:177]
	v_add_co_u32_e32 v6, vcc, s2, v6
	v_lshl_add_u64 v[10:11], v[10:11], 0, v[40:41]
	v_lshl_add_u64 v[4:5], v[4:5], 0, v[40:41]
	v_addc_co_u32_e32 v7, vcc, 0, v7, vcc
	s_nop 0
	s_nop 0
	global_load_ushort v168, v[10:11], off offset:3840
	global_load_ushort v169, v[42:43], off offset:3840
	global_load_ushort v170, v[58:59], off offset:3840
	global_load_ushort v171, v[84:85], off offset:3840
	s_nop 0
	s_nop 0
	global_load_ushort v172, v[156:157], off offset:3840
	global_load_ushort v173, v[160:161], off offset:3840
	s_nop 0
	global_load_ushort v162, v[164:165], off offset:3840
	global_load_ushort v163, v[4:5], off offset:3840
	global_load_dwordx4 v[8:11], v[6:7], off
	s_nop 0
	s_nop 0
	global_load_dwordx4 v[4:7], v[158:159], off offset:16
	v_lshl_add_u64 v[158:159], s[82:83], 0, v[104:105]
	v_lshlrev_b32_e32 v104, 2, v166
	v_or3_b32 v160, v109, s8, v166
	v_lshl_add_u64 v[158:159], v[158:159], 0, v[104:105]
	v_ashrrev_i32_e32 v161, 31, v160
	v_add_co_u32_e32 v158, vcc, s2, v158
	v_lshl_add_u64 v[160:161], v[160:161], 2, s[50:51]
	s_nop 0
	v_addc_co_u32_e32 v159, vcc, 0, v159, vcc
	global_load_dword v160, v[160:161], off
	s_nop 0
	s_nop 0
	s_waitcnt vmcnt(0)
	s_barrier
	s_mov_b32 s3, 0xbfb8aa3b
	s_mov_b32 s2, 0x3d800000
	v_cmp_gt_u32_sdwa s[4:5], v115, v219 src0_sel:BYTE_0 src1_sel:DWORD
	v_mfma_f32_16x16x4_f32 v[128:131], v140, v118, 0
	v_mfma_f32_16x16x4_f32 v[128:131], v141, v120, v[128:131]
	v_mfma_f32_16x16x4_f32 v[128:131], v142, v122, v[128:131]
	v_mfma_f32_16x16x4_f32 v[128:131], v143, v124, v[128:131]
	v_mfma_f32_16x16x4_f32 v[132:135], v140, v119, 0
	v_mfma_f32_16x16x4_f32 v[132:135], v141, v121, v[132:135]
	v_mfma_f32_16x16x4_f32 v[132:135], v142, v123, v[132:135]
	v_mfma_f32_16x16x4_f32 v[132:135], v143, v125, v[132:135]
	s_nop 15
	s_nop 15
	s_nop 7
	v_permlane16_swap_b32 v128, v132
	v_permlane16_swap_b32 v129, v133
	v_permlane16_swap_b32 v130, v134
	v_permlane16_swap_b32 v131, v135
	v_add_f32_e32 v118, v128, v160
	v_mul_f32_e64 v105, |v118|, s3
	v_exp_f32_e32 v105, v105
	v_add_f32_e32 v68, v131, v160
	v_add_f32_e32 v105, 1.0, v105
	v_mul_f32_e64 v69, |v68|, s3
	v_log_f32_e32 v120, v105
	v_exp_f32_e32 v69, v69
	v_add_f32_e32 v36, v133, v160
	v_mul_f32_e64 v37, |v36|, s3
	v_exp_f32_e32 v37, v37
	v_min_f32_e32 v118, 0, v118
	v_fmac_f32_e32 v118, 0xbf317218, v120
	v_mul_u32_u24_e32 v123, 0x108, v103
	v_add_f32_e32 v69, 1.0, v69
	v_lshrrev_b32_e32 v119, 8, v106
	v_fma_f32 v118, v118, s2, 0
	v_add_lshl_u32 v123, v123, v166, 2
	s_mov_b32 s2, 0xd800
	v_log_f32_e32 v69, v69
	v_lshlrev_b32_e32 v120, 16, v168
	v_add_f32_e32 v121, v129, v160
	v_mad_i32_i24 v123, v119, s2, v123
	v_add_f32_e32 v37, 1.0, v37
	v_mul_f32_e64 v122, |v121|, s3
	ds_write2st64_b32 v123, v118, v120 offset1:68
	v_min_f32_e32 v120, 0, v121
	v_log_f32_e32 v37, v37
	v_min_f32_e32 v68, 0, v68
	v_fmac_f32_e32 v68, 0xbf317218, v69
	v_min_f32_e32 v36, 0, v36
	v_fmac_f32_e32 v36, 0xbf317218, v37
	v_add_f32_e32 v88, v130, v160
	v_exp_f32_e32 v122, v122
	v_mul_f32_e64 v89, |v88|, s3
	v_exp_f32_e32 v89, v89
	v_add_f32_e32 v60, v132, v160
	v_mul_f32_e64 v61, |v60|, s3
	v_exp_f32_e32 v61, v61
	v_add_f32_e32 v28, v134, v160
	v_add_f32_e32 v122, 1.0, v122
	v_mul_f32_e64 v29, |v28|, s3
	v_add_f32_e32 v12, v135, v160
	v_log_f32_e32 v122, v122
	v_add_f32_e32 v89, 1.0, v89
	v_exp_f32_e32 v29, v29
	v_mul_f32_e64 v13, |v12|, s3
	v_log_f32_e32 v89, v89
	v_exp_f32_e32 v13, v13
	v_add_f32_e32 v61, 1.0, v61
	v_log_f32_e32 v61, v61
	v_fmac_f32_e32 v120, 0xbf317218, v122
	v_mul_u32_u24_e32 v91, 33, v167
	v_min_f32_e32 v88, 0, v88
	v_add_f32_e32 v29, 1.0, v29
	v_fmac_f32_e32 v118, 0x3d800000, v120
	v_add_lshl_u32 v91, v91, v166, 2
	v_fmac_f32_e32 v88, 0xbf317218, v89
	v_log_f32_e32 v29, v29
	v_add_f32_e32 v13, 1.0, v13
	v_mad_i32_i24 v91, v119, s2, v91
	v_fmamk_f32 v71, v88, 0x3d800000, v118
	v_min_f32_e32 v60, 0, v60
	v_log_f32_e32 v13, v13
	ds_write2_b32 v91, v118, v71 offset1:33
	v_fmac_f32_e32 v71, 0x3d800000, v68
	v_fmac_f32_e32 v60, 0xbf317218, v61
	v_lshlrev_b32_e32 v90, 16, v169
	v_lshlrev_b32_e32 v70, 16, v170
	v_add_u32_e32 v72, 0x4400, v91
	v_fmamk_f32 v39, v60, 0x3d800000, v71
	v_min_f32_e32 v28, 0, v28
	ds_write2_b32 v72, v90, v70 offset1:33
	v_lshlrev_b32_e32 v62, 16, v171
	v_lshlrev_b32_e32 v38, 16, v172
	ds_write2_b32 v91, v71, v39 offset0:66 offset1:99
	ds_write2_b32 v72, v62, v38 offset0:66 offset1:99
	v_fmac_f32_e32 v39, 0x3d800000, v36
	v_fmac_f32_e32 v28, 0xbf317218, v29
	v_min_f32_e32 v12, 0, v12
	v_fmamk_f32 v15, v28, 0x3d800000, v39
	v_fmac_f32_e32 v12, 0xbf317218, v13
	v_mul_i32_i24_e32 v105, 0xd800, v119
	v_lshlrev_b32_e32 v30, 16, v173
	v_lshlrev_b32_e32 v14, 16, v162
	ds_write2_b32 v91, v39, v15 offset0:132 offset1:165
	ds_write2_b32 v72, v30, v14 offset0:132 offset1:165
	v_fmac_f32_e32 v15, 0x3d800000, v12
	v_lshlrev_b32_e32 v12, 8, v103
	v_or3_b32 v12, v105, v12, v104
	v_lshlrev_b32_e32 v13, 16, v163
	ds_write_b32 v91, v15 offset:792
	ds_write_b32 v91, v13 offset:18200
	ds_write_b32 v12, v15 offset:53248
	v_mul_u32_u24_e32 v12, 0x48, v117
	v_lshlrev_b32_e32 v12, 1, v12
	v_mad_i32_i24 v12, v119, s2, v12
	v_mov_b32_e32 v106, 0
	v_lshl_or_b32 v12, v116, 1, v12
	ds_write_b16 v12, v8 offset:34816
	ds_write_b16_d16_hi v12, v8 offset:34960
	ds_write_b16 v12, v9 offset:35104
	ds_write_b16_d16_hi v12, v9 offset:35248
	ds_write_b16 v12, v10 offset:35392
	ds_write_b16_d16_hi v12, v10 offset:35536
	ds_write_b16 v12, v11 offset:35680
	ds_write_b16_d16_hi v12, v11 offset:35824
	ds_write_b16 v12, v4 offset:35968
	ds_write_b16_d16_hi v12, v4 offset:36112
	ds_write_b16 v12, v5 offset:36256
	ds_write_b16_d16_hi v12, v5 offset:36400
	ds_write_b16 v12, v6 offset:36544
	ds_write_b16_d16_hi v12, v6 offset:36688
	ds_write_b16 v12, v7 offset:36832
	ds_write_b16_d16_hi v12, v7 offset:36976
	s_waitcnt lgkmcnt(0)
	s_barrier
	s_and_saveexec_b64 s[2:3], s[4:5]
	s_cbranch_execz .LBB0_196
	s_mov_b32 s4, 0xd000
	v_add3_u32 v4, v105, v104, s4
	v_mov_b32_e32 v106, 0
	ds_read_b32 v220, v4
	ds_read_b32 v221, v4 offset:256
	ds_read_b32 v222, v4 offset:512
	ds_read_b32 v223, v4 offset:768
	ds_read_b32 v224, v4 offset:1024
	ds_read_b32 v225, v4 offset:1280
	ds_read_b32 v226, v4 offset:1536
	s_waitcnt lgkmcnt(0)
	v_add_f32_e32 v106, v106, v220
	v_cmp_lt_u32_e32 vcc, 1, v103
	s_nop 1
	v_cndmask_b32_e32 v221, 0, v221, vcc
	v_add_f32_e32 v106, v106, v221
	v_cmp_lt_u32_e32 vcc, 2, v103
	s_nop 1
	v_cndmask_b32_e32 v222, 0, v222, vcc
	v_add_f32_e32 v106, v106, v222
	v_cmp_lt_u32_e32 vcc, 3, v103
	s_nop 1
	v_cndmask_b32_e32 v223, 0, v223, vcc
	v_add_f32_e32 v106, v106, v223
	v_cmp_lt_u32_e32 vcc, 4, v103
	s_nop 1
	v_cndmask_b32_e32 v224, 0, v224, vcc
	v_add_f32_e32 v106, v106, v224
	v_cmp_lt_u32_e32 vcc, 5, v103
	s_nop 1
	v_cndmask_b32_e32 v225, 0, v225, vcc
	v_add_f32_e32 v106, v106, v225
	v_cmp_lt_u32_e32 vcc, 6, v103
	s_nop 1
	v_cndmask_b32_e32 v226, 0, v226, vcc
	v_add_f32_e32 v106, v106, v226
	v_mov_b32_e32 v103, 0
